# phase 11 LN1: gamma/beta slices loaded once in front of the row loop, waits recomputed to cover only loads (same treatment as LN2)
# speedup vs baseline: 1.0048x; 1.0048x over previous
.Lp11_ln:
	v_and_b32_e32 v2, 60, v206
	v_lshl_add_u32 v18, s2, 5, v2
	s_movk_i32 s14, 0x4000
	v_cmp_gt_i32_e32 vcc, s14, v18
	s_and_saveexec_b64 s[14:15], vcc
	s_cbranch_execz .LBB0_1365
	v_mbcnt_lo_u32_b32 v3, -1, 0
	v_mbcnt_hi_u32_b32 v3, -1, v3
	v_and_b32_e32 v7, 64, v3
	v_add_u32_e32 v7, 64, v7
	v_xor_b32_e32 v8, 32, v3
	v_cmp_lt_i32_e32 vcc, v8, v7
	v_lshlrev_b32_e32 v2, 3, v1
	v_and_b32_e32 v2, 0x1f8, v2
	v_cndmask_b32_e32 v8, v3, v8, vcc
	v_lshlrev_b32_e32 v71, 2, v8
	v_xor_b32_e32 v8, 16, v3
	v_cmp_lt_i32_e32 vcc, v8, v7
	v_mov_b32_e32 v21, 0
	v_lshlrev_b32_e32 v20, 1, v2
	v_cndmask_b32_e32 v8, v3, v8, vcc
	v_lshlrev_b32_e32 v72, 2, v8
	v_xor_b32_e32 v8, 8, v3
	v_cmp_lt_i32_e32 vcc, v8, v7
	v_lshl_add_u64 v[4:5], s[66:67], 0, v[20:21]
	s_lshl_b32 s19, s70, 5
	v_cndmask_b32_e32 v8, v3, v8, vcc
	v_lshlrev_b32_e32 v73, 2, v8
	v_xor_b32_e32 v8, 4, v3
	v_cmp_lt_i32_e32 vcc, v8, v7
	v_lshlrev_b32_e32 v20, 2, v2
	s_waitcnt lgkmcnt(0)
	v_lshl_add_u64 v[24:25], s[4:5], 0, v[20:21]
	v_cndmask_b32_e32 v8, v3, v8, vcc
	v_lshlrev_b32_e32 v74, 2, v8
	v_xor_b32_e32 v8, 2, v3
	v_cmp_lt_i32_e32 vcc, v8, v7
	v_lshl_add_u64 v[26:27], s[6:7], 0, v[20:21]
	s_add_u32 s6, s66, 0x1a00000
	v_cndmask_b32_e32 v8, v3, v8, vcc
	v_lshlrev_b32_e32 v75, 2, v8
	v_xor_b32_e32 v8, 1, v3
	v_cmp_lt_i32_e32 vcc, v8, v7
	s_mov_b64 s[4:5], 0x9c00000
	s_mov_b64 s[16:17], 0x5c00000
	v_or_b32_e32 v6, 0x200, v2
	s_addc_u32 s7, s67, 0
	v_cndmask_b32_e32 v3, v3, v8, vcc
	v_lshl_add_u64 v[28:29], v[4:5], 0, s[4:5]
	s_mov_b64 s[4:5], 0x1c00000
	s_mov_b32 s22, 0x3727c5ac
	v_lshl_add_u64 v[22:23], v[4:5], 0, s[16:17]
	v_lshlrev_b32_e32 v76, 2, v3
	v_lshl_add_u64 v[30:31], v[4:5], 0, s[4:5]
	s_mov_b64 s[4:5], 0
	s_movk_i32 s20, 0x1fff
	s_movk_i32 s21, 0x6000
	v_mov_b64_e32 v[32:33], s[6:7]
	s_mov_b64 s[6:7], 0x4000
	s_mov_b64 s[16:17], 0x3000
	v_lshlrev_b32_e32 v20, 2, v2
	s_mov_b32 s18, 0x3a800000
	v_lshlrev_b32_e32 v34, 2, v6
	v_mov_b32_e32 v35, v21
	v_mov_b64_e32 v[36:37], s[22:23]
	s_mov_b32 s22, 0x800000
	s_movk_i32 s23, 0x3fff
	global_load_dwordx4 v[130:133], v[24:25], off
	global_load_dwordx4 v[134:137], v[24:25], off offset:16
	global_load_dwordx4 v[138:141], v[24:25], off offset:2048
	global_load_dwordx4 v[142:145], v[24:25], off offset:2064
	global_load_dwordx4 v[146:149], v[26:27], off
	global_load_dwordx4 v[150:153], v[26:27], off offset:16
	global_load_dwordx4 v[154:157], v[26:27], off offset:2048
	global_load_dwordx4 v[158:161], v[26:27], off offset:2064
	s_waitcnt vmcnt(0)
.LBB0_1364:
	v_ashrrev_i32_e32 v19, 31, v18
	v_lshlrev_b64 v[40:41], 11, v[18:19]
	v_lshl_add_u64 v[10:11], v[22:23], 0, v[40:41]
	global_load_dwordx4 v[2:5], v[10:11], off
	global_load_dwordx4 v[6:9], v[10:11], off offset:1024
	v_add_u32_e32 v10, 1, v18
	v_ashrrev_i32_e32 v11, 31, v10
	v_lshlrev_b64 v[56:57], 11, v[10:11]
	v_lshl_add_u64 v[38:39], v[22:23], 0, v[56:57]
	global_load_dwordx4 v[10:13], v[38:39], off
	global_load_dwordx4 v[14:17], v[38:39], off offset:1024
	v_cmp_lt_i32_e32 vcc, s20, v18
	v_lshl_add_u64 v[110:111], v[28:29], 0, v[40:41]
	v_lshl_add_u64 v[114:115], v[30:31], 0, v[40:41]
	s_waitcnt vmcnt(0)
	v_lshlrev_b32_e32 v38, 16, v5
	v_and_b32_e32 v39, 0xffff0000, v5
	v_lshlrev_b32_e32 v42, 16, v4
	v_and_b32_e32 v43, 0xffff0000, v4
	v_lshlrev_b32_e32 v4, 16, v3
	v_lshlrev_b32_e32 v58, 16, v10
	v_and_b32_e32 v5, 0xffff0000, v3
	v_lshlrev_b32_e32 v48, 16, v2
	v_and_b32_e32 v49, 0xffff0000, v2
	v_lshlrev_b32_e32 v2, 16, v9
	v_and_b32_e32 v3, 0xffff0000, v9
	v_lshlrev_b32_e32 v50, 16, v8
	v_and_b32_e32 v51, 0xffff0000, v8
	v_lshlrev_b32_e32 v8, 16, v7
	v_and_b32_e32 v9, 0xffff0000, v7
	v_lshlrev_b32_e32 v52, 16, v6
	v_and_b32_e32 v53, 0xffff0000, v6
	v_lshlrev_b32_e32 v6, 16, v13
	v_and_b32_e32 v7, 0xffff0000, v13
	v_lshlrev_b32_e32 v54, 16, v12
	v_and_b32_e32 v55, 0xffff0000, v12
	v_lshlrev_b32_e32 v12, 16, v11
	v_and_b32_e32 v13, 0xffff0000, v11
	v_and_b32_e32 v59, 0xffff0000, v10
	v_lshlrev_b32_e32 v10, 16, v17
	v_and_b32_e32 v11, 0xffff0000, v17
	v_lshlrev_b32_e32 v62, 16, v16
	v_and_b32_e32 v63, 0xffff0000, v16
	v_lshlrev_b32_e32 v16, 16, v15
	v_and_b32_e32 v17, 0xffff0000, v15
	v_add_f32_e32 v15, 0, v58
	v_add_f32_e32 v19, 0, v48
	v_add_f32_e32 v15, v15, v59
	v_lshlrev_b32_e32 v90, 16, v14
	v_and_b32_e32 v91, 0xffff0000, v14
	v_add_f32_e32 v14, v19, v49
	v_add_f32_e32 v15, v15, v12
	v_add_f32_e32 v14, v14, v4
	v_add_f32_e32 v15, v15, v13
	v_add_f32_e32 v14, v14, v5
	v_add_f32_e32 v15, v15, v54
	v_add_f32_e32 v14, v14, v42
	v_add_f32_e32 v15, v15, v55
	v_add_f32_e32 v14, v14, v43
	v_add_f32_e32 v15, v15, v6
	v_add_f32_e32 v14, v14, v38
	v_add_f32_e32 v15, v15, v7
	v_add_f32_e32 v14, v14, v39
	v_add_f32_e32 v15, v15, v90
	v_add_f32_e32 v14, v14, v52
	v_add_f32_e32 v15, v15, v91
	v_add_f32_e32 v14, v14, v53
	v_add_f32_e32 v15, v15, v16
	v_add_f32_e32 v14, v14, v8
	v_add_f32_e32 v15, v15, v17
	v_add_f32_e32 v14, v14, v9
	v_add_f32_e32 v15, v15, v62
	v_add_f32_e32 v14, v14, v50
	v_add_f32_e32 v15, v15, v63
	v_add_f32_e32 v14, v14, v51
	v_add_f32_e32 v15, v15, v10
	v_add_f32_e32 v14, v14, v2
	v_add_f32_e32 v15, v15, v11
	v_add_f32_e32 v14, v14, v3
	ds_bpermute_b32 v44, v71, v15
	ds_bpermute_b32 v19, v71, v14
	s_waitcnt lgkmcnt(1)
	v_add_f32_e32 v15, v15, v44
	s_waitcnt lgkmcnt(0)
	v_add_f32_e32 v14, v14, v19
	ds_bpermute_b32 v44, v72, v15
	ds_bpermute_b32 v19, v72, v14
	s_waitcnt lgkmcnt(1)
	v_add_f32_e32 v15, v15, v44
	s_waitcnt lgkmcnt(0)
	v_add_f32_e32 v14, v14, v19
	ds_bpermute_b32 v44, v73, v15
	ds_bpermute_b32 v19, v73, v14
	s_waitcnt lgkmcnt(1)
	v_add_f32_e32 v15, v15, v44
	s_waitcnt lgkmcnt(0)
	v_add_f32_e32 v14, v14, v19
	ds_bpermute_b32 v44, v74, v15
	ds_bpermute_b32 v19, v74, v14
	s_waitcnt lgkmcnt(1)
	v_add_f32_e32 v15, v15, v44
	v_mov_b32_e32 v44, v134
	v_mov_b32_e32 v45, v135
	v_mov_b32_e32 v46, v136
	v_mov_b32_e32 v47, v137
	v_mov_b32_e32 v78, v130
	v_mov_b32_e32 v79, v131
	v_mov_b32_e32 v80, v132
	v_mov_b32_e32 v81, v133
	v_mov_b32_e32 v82, v150
	v_mov_b32_e32 v83, v151
	v_mov_b32_e32 v84, v152
	v_mov_b32_e32 v85, v153
	v_mov_b32_e32 v86, v146
	v_mov_b32_e32 v87, v147
	v_mov_b32_e32 v88, v148
	v_mov_b32_e32 v89, v149
	s_waitcnt lgkmcnt(0)
	v_add_f32_e32 v14, v14, v19
	ds_bpermute_b32 v19, v75, v14
	ds_bpermute_b32 v60, v75, v15
	s_waitcnt lgkmcnt(1)
	v_add_f32_e32 v14, v14, v19
	ds_bpermute_b32 v19, v76, v14
	s_waitcnt lgkmcnt(1)
	v_add_f32_e32 v15, v15, v60
	ds_bpermute_b32 v60, v76, v15
	s_waitcnt lgkmcnt(1)
	v_add_f32_e32 v14, v14, v19
	v_mul_f32_e32 v14, 0x3a800000, v14
	s_waitcnt lgkmcnt(0)
	v_add_f32_e32 v15, v15, v60
	v_pk_add_f32 v[106:107], v[2:3], v[14:15] op_sel_hi:[1,0] neg_lo:[0,1] neg_hi:[0,1]
	v_mul_f32_e32 v2, 0x3a800000, v15
	v_pk_add_f32 v[92:93], v[48:49], v[14:15] op_sel_hi:[1,0] neg_lo:[0,1] neg_hi:[0,1]
	v_pk_add_f32 v[60:61], v[58:59], v[2:3] op_sel_hi:[1,0] neg_lo:[0,1] neg_hi:[0,1]
	v_pk_add_f32 v[98:99], v[38:39], v[14:15] op_sel_hi:[1,0] neg_lo:[0,1] neg_hi:[0,1]
	v_mov_b32_e32 v39, v93
	v_mov_b32_e32 v38, v61
	v_pk_add_f32 v[94:95], v[4:5], v[14:15] op_sel_hi:[1,0] neg_lo:[0,1] neg_hi:[0,1]
	v_pk_add_f32 v[96:97], v[42:43], v[14:15] op_sel_hi:[1,0] neg_lo:[0,1] neg_hi:[0,1]
	v_pk_add_f32 v[100:101], v[52:53], v[14:15] op_sel_hi:[1,0] neg_lo:[0,1] neg_hi:[0,1]
	v_pk_add_f32 v[102:103], v[8:9], v[14:15] op_sel_hi:[1,0] neg_lo:[0,1] neg_hi:[0,1]
	v_pk_add_f32 v[104:105], v[50:51], v[14:15] op_sel_hi:[1,0] neg_lo:[0,1] neg_hi:[0,1]
	v_mov_b32_e32 v15, v92
	v_pk_add_f32 v[64:65], v[12:13], v[2:3] op_sel_hi:[1,0] neg_lo:[0,1] neg_hi:[0,1]
	v_mov_b32_e32 v14, v60
	v_pk_mul_f32 v[38:39], v[38:39], v[38:39]
	v_mov_b32_e32 v13, v94
	v_mov_b32_e32 v12, v64
	v_pk_fma_f32 v[14:15], v[14:15], v[14:15], v[38:39]
	v_pk_add_f32 v[68:69], v[54:55], v[2:3] op_sel_hi:[1,0] neg_lo:[0,1] neg_hi:[0,1]
	v_pk_add_f32 v[66:67], v[6:7], v[2:3] op_sel_hi:[1,0] neg_lo:[0,1] neg_hi:[0,1]
	v_mov_b32_e32 v7, v95
	v_mov_b32_e32 v6, v65
	v_pk_fma_f32 v[12:13], v[12:13], v[12:13], v[14:15]
	v_pk_add_f32 v[50:51], v[16:17], v[2:3] op_sel_hi:[1,0] neg_lo:[0,1] neg_hi:[0,1]
	v_mov_b32_e32 v17, v96
	v_mov_b32_e32 v16, v68
	v_pk_fma_f32 v[6:7], v[6:7], v[6:7], v[12:13]
	v_mov_b32_e32 v43, v97
	v_mov_b32_e32 v42, v69
	v_pk_fma_f32 v[6:7], v[16:17], v[16:17], v[6:7]
	v_mov_b32_e32 v49, v98
	v_mov_b32_e32 v48, v66
	v_pk_fma_f32 v[6:7], v[42:43], v[42:43], v[6:7]
	v_pk_add_f32 v[52:53], v[90:91], v[2:3] op_sel_hi:[1,0] neg_lo:[0,1] neg_hi:[0,1]
	v_mov_b32_e32 v59, v99
	v_mov_b32_e32 v58, v67
	v_pk_fma_f32 v[6:7], v[48:49], v[48:49], v[6:7]
	v_mov_b32_e32 v90, v52
	v_pk_fma_f32 v[6:7], v[58:59], v[58:59], v[6:7]
	v_mov_b32_e32 v91, v100
	v_pk_fma_f32 v[6:7], v[90:91], v[90:91], v[6:7]
	v_mov_b32_e32 v12, v53
	v_mov_b32_e32 v13, v101
	v_pk_add_f32 v[54:55], v[62:63], v[2:3] op_sel_hi:[1,0] neg_lo:[0,1] neg_hi:[0,1]
	v_pk_fma_f32 v[6:7], v[12:13], v[12:13], v[6:7]
	v_mov_b32_e32 v12, v50
	v_mov_b32_e32 v13, v102
	v_pk_mul_f32 v[4:5], v[104:105], v[104:105]
	v_pk_mul_f32 v[62:63], v[54:55], v[54:55]
	v_pk_fma_f32 v[6:7], v[12:13], v[12:13], v[6:7]
	v_mov_b32_e32 v12, v51
	v_mov_b32_e32 v13, v103
	v_pk_fma_f32 v[6:7], v[12:13], v[12:13], v[6:7]
	v_mov_b32_e32 v12, v62
	v_mov_b32_e32 v13, v4
	v_pk_add_f32 v[58:59], v[10:11], v[2:3] op_sel_hi:[1,0] neg_lo:[0,1] neg_hi:[0,1]
	v_pk_mul_f32 v[8:9], v[106:107], v[106:107]
	v_pk_add_f32 v[6:7], v[12:13], v[6:7]
	v_pk_mul_f32 v[2:3], v[58:59], v[58:59]
	v_mov_b32_e32 v4, v63
	v_pk_add_f32 v[4:5], v[4:5], v[6:7]
	v_mov_b32_e32 v6, v2
	v_mov_b32_e32 v7, v8
	v_pk_add_f32 v[4:5], v[6:7], v[4:5]
	v_mov_b32_e32 v8, v3
	v_pk_add_f32 v[2:3], v[8:9], v[4:5]
	ds_bpermute_b32 v5, v71, v3
	ds_bpermute_b32 v4, v71, v2
	v_add_u32_e32 v6, 2, v18
	v_ashrrev_i32_e32 v7, 31, v6
	v_lshlrev_b64 v[48:49], 11, v[6:7]
	v_lshl_add_u64 v[6:7], v[22:23], 0, v[48:49]
	s_waitcnt lgkmcnt(0)
	v_pk_add_f32 v[2:3], v[2:3], v[4:5]
	ds_bpermute_b32 v5, v72, v3
	ds_bpermute_b32 v4, v72, v2
	global_load_dwordx4 v[14:17], v[6:7], off
	global_load_dwordx4 v[10:13], v[6:7], off offset:1024
	v_add_u32_e32 v6, 3, v18
	v_ashrrev_i32_e32 v7, 31, v6
	v_lshlrev_b64 v[38:39], 11, v[6:7]
	s_waitcnt lgkmcnt(0)
	v_pk_add_f32 v[2:3], v[2:3], v[4:5]
	ds_bpermute_b32 v5, v73, v3
	ds_bpermute_b32 v4, v73, v2
	v_lshl_add_u64 v[42:43], v[22:23], 0, v[38:39]
	v_add_u32_e32 v19, 0xffffe000, v18
	v_lshrrev_b32_e32 v19, 12, v19
	v_add_u32_e32 v19, 1, v19
	s_waitcnt lgkmcnt(0)
	v_pk_add_f32 v[2:3], v[2:3], v[4:5]
	ds_bpermute_b32 v5, v74, v3
	ds_bpermute_b32 v4, v74, v2
	v_cndmask_b32_e32 v19, 0, v19, vcc
	v_add_u32_e32 v18, s19, v18
	s_waitcnt lgkmcnt(0)
	v_pk_add_f32 v[62:63], v[2:3], v[4:5]
	ds_bpermute_b32 v91, v75, v63
	ds_bpermute_b32 v90, v75, v62
	global_load_dwordx4 v[6:9], v[42:43], off
	global_load_dwordx4 v[2:5], v[42:43], off offset:1024
	s_waitcnt lgkmcnt(0)
	v_pk_add_f32 v[42:43], v[62:63], v[90:91]
	ds_bpermute_b32 v63, v76, v43
	ds_bpermute_b32 v62, v76, v42
	v_mad_u64_u32 v[90:91], s[24:25], v19, s21, v[32:33]
	v_lshl_add_u64 v[108:109], v[90:91], 0, s[6:7]
	s_waitcnt lgkmcnt(0)
	v_pk_add_f32 v[42:43], v[42:43], v[62:63]
	s_nop 0
	v_pk_fma_f32 v[62:63], v[42:43], s[18:19], v[36:37] op_sel_hi:[1,0,0]
	v_lshl_add_u64 v[42:43], v[108:109], 0, v[20:21]
	v_mul_f32_e32 v19, 0x4b800000, v63
	v_cmp_gt_f32_e32 vcc, s22, v63
	s_nop 1
	v_cndmask_b32_e32 v19, v63, v19, vcc
	v_rsq_f32_e32 v19, v19
	s_nop 0
	v_mul_f32_e32 v63, 0x45800000, v19
	v_cndmask_b32_e32 v70, v19, v63, vcc
	v_pk_mul_f32 v[92:93], v[92:93], v[70:71] op_sel_hi:[1,0]
	v_mul_f32_e32 v19, 0x4b800000, v62
	s_waitcnt vmcnt(4)
	v_pk_fma_f32 v[112:113], v[78:79], v[92:93], v[86:87]
	v_pk_mul_f32 v[78:79], v[96:97], v[70:71] op_sel_hi:[1,0]
	v_cmp_gt_f32_e32 vcc, s22, v62
	v_pk_fma_f32 v[96:97], v[44:45], v[78:79], v[82:83]
	v_pk_mul_f32 v[44:45], v[94:95], v[70:71] op_sel_hi:[1,0]
	v_cndmask_b32_e32 v19, v62, v19, vcc
	v_pk_fma_f32 v[94:95], v[80:81], v[44:45], v[88:89]
	v_pk_mul_f32 v[44:45], v[98:99], v[70:71] op_sel_hi:[1,0]
	v_rsq_f32_e32 v19, v19
	v_pk_fma_f32 v[98:99], v[46:47], v[44:45], v[84:85]
	v_cvt_pk_bf16_f32 v44, v112, v113
	v_cvt_pk_bf16_f32 v45, v94, v95
	v_cvt_pk_bf16_f32 v46, v96, v97
	v_cvt_pk_bf16_f32 v47, v98, v99
	global_store_dwordx4 v[110:111], v[44:47], off
	global_load_dwordx4 v[78:81], v[42:43], off
	global_load_dwordx4 v[82:85], v[42:43], off offset:16
	v_lshl_add_u64 v[46:47], v[90:91], 0, s[16:17]
	v_lshl_add_u64 v[44:45], v[46:47], 0, v[20:21]
	global_load_dwordx4 v[86:89], v[44:45], off
	global_load_dwordx4 v[90:93], v[44:45], off offset:16
	v_lshl_add_u64 v[46:47], v[46:47], 0, v[34:35]
	v_lshl_add_u64 v[62:63], v[28:29], 0, v[56:57]
	v_lshl_add_u64 v[56:57], v[30:31], 0, v[56:57]
	s_waitcnt vmcnt(3)
	v_pk_add_f32 v[40:41], v[78:79], 1.0 op_sel_hi:[1,0]
	s_waitcnt vmcnt(2)
	v_pk_add_f32 v[78:79], v[82:83], 1.0 op_sel_hi:[1,0]
	v_pk_add_f32 v[80:81], v[80:81], 1.0 op_sel_hi:[1,0]
	v_pk_add_f32 v[82:83], v[84:85], 1.0 op_sel_hi:[1,0]
	s_waitcnt vmcnt(1)
	v_pk_fma_f32 v[40:41], v[40:41], v[112:113], v[86:87]
	s_waitcnt vmcnt(0)
	v_pk_fma_f32 v[84:85], v[78:79], v[96:97], v[90:91]
	v_pk_fma_f32 v[80:81], v[80:81], v[94:95], v[88:89]
	v_pk_fma_f32 v[82:83], v[82:83], v[98:99], v[92:93]
	v_cvt_pk_bf16_f32 v78, v40, v41
	v_cvt_pk_bf16_f32 v79, v80, v81
	v_cvt_pk_bf16_f32 v80, v84, v85
	v_cvt_pk_bf16_f32 v81, v82, v83
	global_store_dwordx4 v[114:115], v[78:81], off
	s_nop 1
	v_mov_b32_e32 v78, v142
	v_mov_b32_e32 v79, v143
	v_mov_b32_e32 v80, v144
	v_mov_b32_e32 v81, v145
	s_nop 0
	v_mov_b32_e32 v82, v138
	v_mov_b32_e32 v83, v139
	v_mov_b32_e32 v84, v140
	v_mov_b32_e32 v85, v141
	v_mov_b32_e32 v86, v154
	v_mov_b32_e32 v87, v155
	v_mov_b32_e32 v88, v156
	v_mov_b32_e32 v89, v157
	v_mov_b32_e32 v90, v158
	v_mov_b32_e32 v91, v159
	v_mov_b32_e32 v92, v160
	v_mov_b32_e32 v93, v161
	v_pk_mul_f32 v[94:95], v[100:101], v[70:71] op_sel_hi:[1,0]
	v_pk_mul_f32 v[96:97], v[104:105], v[70:71] op_sel_hi:[1,0]
	v_pk_mul_f32 v[98:99], v[102:103], v[70:71] op_sel_hi:[1,0]
	v_pk_mul_f32 v[100:101], v[106:107], v[70:71] op_sel_hi:[1,0]
	v_lshl_add_u64 v[40:41], v[108:109], 0, v[34:35]
	v_mul_f32_e32 v70, 0x45800000, v19
	v_cndmask_b32_e32 v70, v19, v70, vcc
	v_pk_mul_f32 v[60:61], v[60:61], v[70:71] op_sel_hi:[1,0]
	v_pk_mul_f32 v[68:69], v[68:69], v[70:71] op_sel_hi:[1,0]
	v_pk_mul_f32 v[64:65], v[64:65], v[70:71] op_sel_hi:[1,0]
	v_pk_mul_f32 v[66:67], v[66:67], v[70:71] op_sel_hi:[1,0]
	v_lshlrev_b32_e32 v106, 16, v3
	v_and_b32_e32 v107, 0xffff0000, v3
	v_lshlrev_b32_e32 v108, 16, v2
	v_and_b32_e32 v109, 0xffff0000, v2
	v_lshlrev_b32_e32 v102, 16, v8
	v_and_b32_e32 v103, 0xffff0000, v8
	v_lshlrev_b32_e32 v8, 16, v7
	v_lshlrev_b32_e32 v104, 16, v5
	v_and_b32_e32 v105, 0xffff0000, v5
	v_pk_mul_f32 v[50:51], v[50:51], v[70:71] op_sel_hi:[1,0]
	s_waitcnt vmcnt(1)
	v_pk_fma_f32 v[94:95], v[82:83], v[94:95], v[86:87]
	s_waitcnt vmcnt(1)
	v_pk_fma_f32 v[96:97], v[78:79], v[96:97], v[90:91]
	v_pk_fma_f32 v[98:99], v[84:85], v[98:99], v[88:89]
	v_pk_fma_f32 v[100:101], v[80:81], v[100:101], v[92:93]
	v_cvt_pk_bf16_f32 v78, v94, v95
	v_cvt_pk_bf16_f32 v79, v98, v99
	v_cvt_pk_bf16_f32 v80, v96, v97
	v_cvt_pk_bf16_f32 v81, v100, v101
	global_store_dwordx4 v[110:111], v[78:81], off offset:1024
	global_load_dwordx4 v[78:81], v[40:41], off
	s_nop 0
	global_load_dwordx4 v[82:85], v[40:41], off offset:16
	global_load_dwordx4 v[86:89], v[46:47], off
	global_load_dwordx4 v[90:93], v[46:47], off offset:16
	s_waitcnt vmcnt(3)
	v_pk_add_f32 v[78:79], v[78:79], 1.0 op_sel_hi:[1,0]
	s_waitcnt vmcnt(2)
	v_pk_add_f32 v[82:83], v[82:83], 1.0 op_sel_hi:[1,0]
	v_pk_add_f32 v[80:81], v[80:81], 1.0 op_sel_hi:[1,0]
	v_pk_add_f32 v[84:85], v[84:85], 1.0 op_sel_hi:[1,0]
	s_waitcnt vmcnt(1)
	v_pk_fma_f32 v[78:79], v[78:79], v[94:95], v[86:87]
	s_waitcnt vmcnt(0)
	v_pk_fma_f32 v[82:83], v[82:83], v[96:97], v[90:91]
	v_pk_fma_f32 v[80:81], v[80:81], v[98:99], v[88:89]
	v_pk_fma_f32 v[84:85], v[84:85], v[100:101], v[92:93]
	v_cvt_pk_bf16_f32 v78, v78, v79
	v_cvt_pk_bf16_f32 v79, v80, v81
	v_cvt_pk_bf16_f32 v80, v82, v83
	v_cvt_pk_bf16_f32 v81, v84, v85
	global_store_dwordx4 v[114:115], v[78:81], off offset:1024
	s_nop 1
	v_mov_b32_e32 v78, v134
	v_mov_b32_e32 v79, v135
	v_mov_b32_e32 v80, v136
	v_mov_b32_e32 v81, v137
	s_nop 0
	v_mov_b32_e32 v82, v130
	v_mov_b32_e32 v83, v131
	v_mov_b32_e32 v84, v132
	v_mov_b32_e32 v85, v133
	v_mov_b32_e32 v86, v146
	v_mov_b32_e32 v87, v147
	v_mov_b32_e32 v88, v148
	v_mov_b32_e32 v89, v149
	v_mov_b32_e32 v90, v150
	v_mov_b32_e32 v91, v151
	v_mov_b32_e32 v92, v152
	v_mov_b32_e32 v93, v153
	v_lshlrev_b32_e32 v94, 16, v14
	v_lshlrev_b32_e32 v98, 16, v10
	v_and_b32_e32 v99, 0xffff0000, v10
	v_lshlrev_b32_e32 v10, 16, v6
	v_and_b32_e32 v95, 0xffff0000, v14
	v_lshlrev_b32_e32 v14, 16, v13
	v_lshlrev_b32_e32 v96, 16, v12
	v_and_b32_e32 v97, 0xffff0000, v12
	v_lshlrev_b32_e32 v12, 16, v11
	v_add_f32_e32 v2, 0, v94
	v_add_f32_e32 v3, 0, v10
	v_add_f32_e32 v2, v2, v95
	v_lshlrev_b32_e32 v100, 16, v9
	v_and_b32_e32 v101, 0xffff0000, v9
	v_and_b32_e32 v9, 0xffff0000, v7
	v_and_b32_e32 v7, 0xffff0000, v4
	s_waitcnt vmcnt(1)
	v_pk_fma_f32 v[60:61], v[82:83], v[60:61], v[86:87]
	s_waitcnt vmcnt(1)
	v_pk_fma_f32 v[68:69], v[78:79], v[68:69], v[90:91]
	v_pk_fma_f32 v[90:91], v[84:85], v[64:65], v[88:89]
	v_pk_fma_f32 v[92:93], v[80:81], v[66:67], v[92:93]
	v_cvt_pk_bf16_f32 v64, v60, v61
	v_cvt_pk_bf16_f32 v65, v90, v91
	v_cvt_pk_bf16_f32 v66, v68, v69
	v_cvt_pk_bf16_f32 v67, v92, v93
	global_store_dwordx4 v[62:63], v[64:67], off
	global_load_dwordx4 v[64:67], v[42:43], off
	s_nop 0
	global_load_dwordx4 v[78:81], v[42:43], off offset:16
	global_load_dwordx4 v[82:85], v[44:45], off
	global_load_dwordx4 v[86:89], v[44:45], off offset:16
	s_waitcnt vmcnt(3)
	v_pk_add_f32 v[64:65], v[64:65], 1.0 op_sel_hi:[1,0]
	s_waitcnt vmcnt(2)
	v_pk_add_f32 v[78:79], v[78:79], 1.0 op_sel_hi:[1,0]
	v_pk_add_f32 v[66:67], v[66:67], 1.0 op_sel_hi:[1,0]
	v_pk_add_f32 v[80:81], v[80:81], 1.0 op_sel_hi:[1,0]
	s_waitcnt vmcnt(1)
	v_pk_fma_f32 v[60:61], v[64:65], v[60:61], v[82:83]
	s_waitcnt vmcnt(0)
	v_pk_fma_f32 v[68:69], v[78:79], v[68:69], v[86:87]
	v_pk_fma_f32 v[66:67], v[66:67], v[90:91], v[84:85]
	v_pk_fma_f32 v[78:79], v[80:81], v[92:93], v[88:89]
	v_cvt_pk_bf16_f32 v64, v60, v61
	v_cvt_pk_bf16_f32 v65, v66, v67
	v_cvt_pk_bf16_f32 v66, v68, v69
	v_cvt_pk_bf16_f32 v67, v78, v79
	global_store_dwordx4 v[56:57], v[64:67], off
	s_nop 1
	v_mov_b32_e32 v64, v142
	v_mov_b32_e32 v65, v143
	v_mov_b32_e32 v66, v144
	v_mov_b32_e32 v67, v145
	s_nop 0
	v_mov_b32_e32 v78, v138
	v_mov_b32_e32 v79, v139
	v_mov_b32_e32 v80, v140
	v_mov_b32_e32 v81, v141
	v_mov_b32_e32 v82, v154
	v_mov_b32_e32 v83, v155
	v_mov_b32_e32 v84, v156
	v_mov_b32_e32 v85, v157
	v_mov_b32_e32 v86, v158
	v_mov_b32_e32 v87, v159
	v_mov_b32_e32 v88, v160
	v_mov_b32_e32 v89, v161
	v_lshlrev_b32_e32 v90, 16, v17
	v_and_b32_e32 v91, 0xffff0000, v17
	v_lshlrev_b32_e32 v92, 16, v16
	v_and_b32_e32 v93, 0xffff0000, v16
	v_lshlrev_b32_e32 v16, 16, v15
	v_and_b32_e32 v17, 0xffff0000, v15
	v_and_b32_e32 v15, 0xffff0000, v13
	v_and_b32_e32 v13, 0xffff0000, v11
	v_and_b32_e32 v11, 0xffff0000, v6
	v_add_f32_e32 v3, v3, v11
	v_add_f32_e32 v2, v2, v16
	v_add_f32_e32 v3, v3, v8
	v_add_f32_e32 v2, v2, v17
	v_add_f32_e32 v3, v3, v9
	v_add_f32_e32 v2, v2, v92
	v_add_f32_e32 v3, v3, v102
	v_add_f32_e32 v2, v2, v93
	v_add_f32_e32 v3, v3, v103
	v_add_f32_e32 v2, v2, v90
	v_add_f32_e32 v3, v3, v100
	v_add_f32_e32 v2, v2, v91
	v_add_f32_e32 v3, v3, v101
	v_add_f32_e32 v2, v2, v98
	v_add_f32_e32 v3, v3, v108
	v_add_f32_e32 v2, v2, v99
	v_add_f32_e32 v3, v3, v109
	v_add_f32_e32 v2, v2, v12
	v_add_f32_e32 v3, v3, v106
	v_lshlrev_b32_e32 v6, 16, v4
	v_add_f32_e32 v2, v2, v13
	v_add_f32_e32 v3, v3, v107
	v_add_f32_e32 v2, v2, v96
	v_add_f32_e32 v3, v3, v6
	v_add_f32_e32 v2, v2, v97
	v_add_f32_e32 v3, v3, v7
	v_add_f32_e32 v2, v2, v14
	v_add_f32_e32 v3, v3, v104
	v_add_f32_e32 v2, v2, v15
	v_add_f32_e32 v3, v3, v105
	ds_bpermute_b32 v4, v71, v2
	ds_bpermute_b32 v5, v71, v3
	s_waitcnt lgkmcnt(1)
	v_add_f32_e32 v19, v2, v4
	s_waitcnt lgkmcnt(0)
	v_add_f32_e32 v77, v3, v5
	v_pk_mul_f32 v[2:3], v[52:53], v[70:71] op_sel_hi:[1,0]
	v_pk_mul_f32 v[4:5], v[54:55], v[70:71] op_sel_hi:[1,0]
	v_pk_mul_f32 v[52:53], v[58:59], v[70:71] op_sel_hi:[1,0]
	ds_bpermute_b32 v110, v72, v19
	s_waitcnt vmcnt(1)
	v_pk_fma_f32 v[54:55], v[78:79], v[2:3], v[82:83]
	s_waitcnt vmcnt(1)
	v_pk_fma_f32 v[78:79], v[64:65], v[4:5], v[86:87]
	v_pk_fma_f32 v[80:81], v[80:81], v[50:51], v[84:85]
	v_pk_fma_f32 v[82:83], v[66:67], v[52:53], v[88:89]
	v_cvt_pk_bf16_f32 v2, v54, v55
	v_cvt_pk_bf16_f32 v3, v80, v81
	v_cvt_pk_bf16_f32 v4, v78, v79
	v_cvt_pk_bf16_f32 v5, v82, v83
	global_store_dwordx4 v[62:63], v[2:5], off offset:1024
	global_load_dwordx4 v[50:53], v[40:41], off offset:16
	global_load_dwordx4 v[58:61], v[40:41], off
	s_nop 0
	global_load_dwordx4 v[62:65], v[46:47], off offset:16
	global_load_dwordx4 v[66:69], v[46:47], off
	ds_bpermute_b32 v2, v72, v77
	s_waitcnt lgkmcnt(1)
	v_add_f32_e32 v3, v19, v110
	ds_bpermute_b32 v4, v73, v3
	s_waitcnt lgkmcnt(1)
	v_add_f32_e32 v2, v77, v2
	ds_bpermute_b32 v5, v73, v2
	s_waitcnt lgkmcnt(1)
	v_add_f32_e32 v3, v3, v4
	ds_bpermute_b32 v4, v74, v3
	s_waitcnt lgkmcnt(1)
	v_add_f32_e32 v2, v2, v5
	ds_bpermute_b32 v5, v74, v2
	s_waitcnt lgkmcnt(1)
	v_add_f32_e32 v3, v3, v4
	ds_bpermute_b32 v4, v75, v3
	s_waitcnt lgkmcnt(1)
	v_add_f32_e32 v2, v2, v5
	ds_bpermute_b32 v5, v75, v2
	s_waitcnt lgkmcnt(1)
	v_add_f32_e32 v3, v3, v4
	ds_bpermute_b32 v4, v76, v3
	s_waitcnt lgkmcnt(1)
	v_add_f32_e32 v2, v2, v5
	ds_bpermute_b32 v5, v76, v2
	s_waitcnt lgkmcnt(1)
	v_add_f32_e32 v3, v3, v4
	s_waitcnt lgkmcnt(0)
	v_add_f32_e32 v4, v2, v5
	v_mul_f32_e32 v2, 0x3a800000, v3
	v_mul_f32_e32 v70, 0x3a800000, v4
	v_pk_add_f32 v[84:85], v[94:95], v[2:3] op_sel_hi:[1,0] neg_lo:[0,1] neg_hi:[0,1]
	v_pk_add_f32 v[10:11], v[10:11], v[70:71] op_sel_hi:[1,0] neg_lo:[0,1] neg_hi:[0,1]
	v_pk_add_f32 v[86:87], v[16:17], v[2:3] op_sel_hi:[1,0] neg_lo:[0,1] neg_hi:[0,1]
	v_pk_add_f32 v[88:89], v[92:93], v[2:3] op_sel_hi:[1,0] neg_lo:[0,1] neg_hi:[0,1]
	v_pk_add_f32 v[90:91], v[90:91], v[2:3] op_sel_hi:[1,0] neg_lo:[0,1] neg_hi:[0,1]
	v_pk_add_f32 v[92:93], v[98:99], v[2:3] op_sel_hi:[1,0] neg_lo:[0,1] neg_hi:[0,1]
	v_pk_add_f32 v[94:95], v[12:13], v[2:3] op_sel_hi:[1,0] neg_lo:[0,1] neg_hi:[0,1]
	v_pk_add_f32 v[96:97], v[96:97], v[2:3] op_sel_hi:[1,0] neg_lo:[0,1] neg_hi:[0,1]
	v_pk_add_f32 v[98:99], v[14:15], v[2:3] op_sel_hi:[1,0] neg_lo:[0,1] neg_hi:[0,1]
	v_pk_add_f32 v[12:13], v[8:9], v[70:71] op_sel_hi:[1,0] neg_lo:[0,1] neg_hi:[0,1]
	v_pk_add_f32 v[2:3], v[106:107], v[70:71] op_sel_hi:[1,0] neg_lo:[0,1] neg_hi:[0,1]
	v_pk_add_f32 v[8:9], v[104:105], v[70:71] op_sel_hi:[1,0] neg_lo:[0,1] neg_hi:[0,1]
	v_mov_b32_e32 v106, v11
	v_mov_b32_e32 v107, v85
	v_pk_add_f32 v[16:17], v[102:103], v[70:71] op_sel_hi:[1,0] neg_lo:[0,1] neg_hi:[0,1]
	v_pk_mul_f32 v[102:103], v[98:99], v[98:99]
	v_mov_b32_e32 v104, v10
	v_mov_b32_e32 v105, v84
	v_pk_add_f32 v[4:5], v[108:109], v[70:71] op_sel_hi:[1,0] neg_lo:[0,1] neg_hi:[0,1]
	v_mov_b32_e32 v108, v12
	v_mov_b32_e32 v109, v86
	v_mov_b32_e32 v112, v13
	v_mov_b32_e32 v113, v87
	v_mov_b32_e32 v114, v16
	v_mov_b32_e32 v115, v88
	v_pk_add_f32 v[14:15], v[100:101], v[70:71] op_sel_hi:[1,0] neg_lo:[0,1] neg_hi:[0,1]
	v_mov_b32_e32 v116, v17
	v_mov_b32_e32 v117, v89
	v_mov_b32_e32 v118, v14
	v_mov_b32_e32 v119, v90
	v_mov_b32_e32 v120, v15
	v_mov_b32_e32 v121, v91
	v_mov_b32_e32 v122, v4
	v_mov_b32_e32 v123, v92
	v_mov_b32_e32 v124, v5
	v_mov_b32_e32 v125, v93
	v_pk_add_f32 v[6:7], v[6:7], v[70:71] op_sel_hi:[1,0] neg_lo:[0,1] neg_hi:[0,1]
	v_mov_b32_e32 v126, v2
	v_mov_b32_e32 v127, v94
	v_pk_mul_f32 v[100:101], v[96:97], v[96:97]
	v_pk_mul_f32 v[110:111], v[6:7], v[6:7]
	v_mov_b32_e32 v128, v3
	v_mov_b32_e32 v129, v95
	s_waitcnt vmcnt(3)
	v_pk_add_f32 v[50:51], v[50:51], 1.0 op_sel_hi:[1,0]
	s_waitcnt vmcnt(2)
	v_pk_add_f32 v[58:59], v[58:59], 1.0 op_sel_hi:[1,0]
	v_pk_add_f32 v[60:61], v[60:61], 1.0 op_sel_hi:[1,0]
	v_pk_add_f32 v[52:53], v[52:53], 1.0 op_sel_hi:[1,0]
	s_waitcnt vmcnt(0)
	v_pk_fma_f32 v[54:55], v[58:59], v[54:55], v[66:67]
	v_pk_fma_f32 v[58:59], v[50:51], v[78:79], v[62:63]
	v_pk_fma_f32 v[60:61], v[60:61], v[80:81], v[68:69]
	v_pk_fma_f32 v[62:63], v[52:53], v[82:83], v[64:65]
	v_cvt_pk_bf16_f32 v50, v54, v55
	v_cvt_pk_bf16_f32 v51, v60, v61
	v_cvt_pk_bf16_f32 v52, v58, v59
	v_cvt_pk_bf16_f32 v53, v62, v63
	global_store_dwordx4 v[56:57], v[50:53], off offset:1024
	s_nop 1
	v_mov_b32_e32 v50, v134
	v_mov_b32_e32 v51, v135
	v_mov_b32_e32 v52, v136
	v_mov_b32_e32 v53, v137
	s_nop 0
	v_mov_b32_e32 v54, v130
	v_mov_b32_e32 v55, v131
	v_mov_b32_e32 v56, v132
	v_mov_b32_e32 v57, v133
	v_mov_b32_e32 v58, v150
	v_mov_b32_e32 v59, v151
	v_mov_b32_e32 v60, v152
	v_mov_b32_e32 v61, v153
	v_mov_b32_e32 v62, v146
	v_mov_b32_e32 v63, v147
	v_mov_b32_e32 v64, v148
	v_mov_b32_e32 v65, v149
	v_pk_mul_f32 v[66:67], v[8:9], v[8:9]
	v_pk_mul_f32 v[68:69], v[106:107], v[106:107]
	v_mov_b32_e32 v80, v66
	v_mov_b32_e32 v81, v102
	v_mov_b32_e32 v102, v67
	v_pk_fma_f32 v[66:67], v[104:105], v[104:105], v[68:69]
	v_mov_b32_e32 v78, v110
	v_pk_fma_f32 v[66:67], v[108:109], v[108:109], v[66:67]
	v_mov_b32_e32 v79, v100
	v_pk_fma_f32 v[66:67], v[112:113], v[112:113], v[66:67]
	v_mov_b32_e32 v100, v111
	v_pk_fma_f32 v[66:67], v[114:115], v[114:115], v[66:67]
	s_nop 0
	v_pk_fma_f32 v[66:67], v[116:117], v[116:117], v[66:67]
	s_nop 0
	v_pk_fma_f32 v[66:67], v[118:119], v[118:119], v[66:67]
	s_nop 0
	v_pk_fma_f32 v[66:67], v[120:121], v[120:121], v[66:67]
	s_nop 0
	v_pk_fma_f32 v[66:67], v[122:123], v[122:123], v[66:67]
	s_nop 0
	v_pk_fma_f32 v[66:67], v[124:125], v[124:125], v[66:67]
	s_nop 0
	v_pk_fma_f32 v[66:67], v[126:127], v[126:127], v[66:67]
	s_nop 0
	v_pk_fma_f32 v[66:67], v[128:129], v[128:129], v[66:67]
	s_nop 0
	v_pk_add_f32 v[66:67], v[78:79], v[66:67]
	s_nop 0
	v_pk_add_f32 v[66:67], v[100:101], v[66:67]
	s_nop 0
	v_pk_add_f32 v[66:67], v[80:81], v[66:67]
	s_nop 0
	v_pk_add_f32 v[66:67], v[102:103], v[66:67]
	ds_bpermute_b32 v69, v71, v67
	ds_bpermute_b32 v68, v71, v66
	s_waitcnt lgkmcnt(0)
	v_pk_add_f32 v[66:67], v[66:67], v[68:69]
	ds_bpermute_b32 v69, v72, v67
	ds_bpermute_b32 v68, v72, v66
	s_waitcnt lgkmcnt(0)
	v_pk_add_f32 v[66:67], v[66:67], v[68:69]
	ds_bpermute_b32 v69, v73, v67
	ds_bpermute_b32 v68, v73, v66
	s_waitcnt lgkmcnt(0)
	v_pk_add_f32 v[66:67], v[66:67], v[68:69]
	ds_bpermute_b32 v69, v74, v67
	ds_bpermute_b32 v68, v74, v66
	s_waitcnt lgkmcnt(0)
	v_pk_add_f32 v[66:67], v[66:67], v[68:69]
	ds_bpermute_b32 v69, v75, v67
	ds_bpermute_b32 v68, v75, v66
	s_waitcnt lgkmcnt(0)
	v_pk_add_f32 v[66:67], v[66:67], v[68:69]
	ds_bpermute_b32 v69, v76, v67
	ds_bpermute_b32 v68, v76, v66
	s_waitcnt lgkmcnt(0)
	v_pk_add_f32 v[66:67], v[66:67], v[68:69]
	s_nop 0
	v_pk_fma_f32 v[66:67], v[66:67], s[18:19], v[36:37] op_sel_hi:[1,0,0]
	v_lshl_add_u64 v[68:69], v[28:29], 0, v[48:49]
	v_mul_f32_e32 v19, 0x4b800000, v67
	v_cmp_gt_f32_e32 vcc, s22, v67
	s_nop 1
	v_cndmask_b32_e32 v19, v67, v19, vcc
	v_rsq_f32_e32 v19, v19
	s_nop 0
	v_mul_f32_e32 v67, 0x45800000, v19
	v_cndmask_b32_e32 v70, v19, v67, vcc
	v_pk_mul_f32 v[78:79], v[84:85], v[70:71] op_sel_hi:[1,0]
	v_pk_mul_f32 v[80:81], v[88:89], v[70:71] op_sel_hi:[1,0]
	v_pk_mul_f32 v[82:83], v[86:87], v[70:71] op_sel_hi:[1,0]
	v_pk_mul_f32 v[84:85], v[90:91], v[70:71] op_sel_hi:[1,0]
	s_waitcnt vmcnt(1)
	v_pk_fma_f32 v[78:79], v[54:55], v[78:79], v[62:63]
	v_pk_fma_f32 v[80:81], v[50:51], v[80:81], v[58:59]
	v_pk_fma_f32 v[82:83], v[56:57], v[82:83], v[64:65]
	v_pk_fma_f32 v[84:85], v[52:53], v[84:85], v[60:61]
	v_cvt_pk_bf16_f32 v50, v78, v79
	v_cvt_pk_bf16_f32 v51, v82, v83
	v_cvt_pk_bf16_f32 v52, v80, v81
	v_cvt_pk_bf16_f32 v53, v84, v85
	global_store_dwordx4 v[68:69], v[50:53], off
	global_load_dwordx4 v[50:53], v[42:43], off
	s_nop 0
	global_load_dwordx4 v[54:57], v[42:43], off offset:16
	global_load_dwordx4 v[58:61], v[44:45], off
	global_load_dwordx4 v[62:65], v[44:45], off offset:16
	v_lshl_add_u64 v[86:87], v[30:31], 0, v[48:49]
	v_mul_f32_e32 v19, 0x4b800000, v66
	v_cmp_gt_f32_e32 vcc, s22, v66
	s_waitcnt vmcnt(3)
	v_pk_add_f32 v[48:49], v[50:51], 1.0 op_sel_hi:[1,0]
	s_waitcnt vmcnt(2)
	v_pk_add_f32 v[50:51], v[54:55], 1.0 op_sel_hi:[1,0]
	v_pk_add_f32 v[52:53], v[52:53], 1.0 op_sel_hi:[1,0]
	v_pk_add_f32 v[54:55], v[56:57], 1.0 op_sel_hi:[1,0]
	s_waitcnt vmcnt(1)
	v_pk_fma_f32 v[48:49], v[48:49], v[78:79], v[58:59]
	s_waitcnt vmcnt(0)
	v_pk_fma_f32 v[50:51], v[50:51], v[80:81], v[62:63]
	v_pk_fma_f32 v[52:53], v[52:53], v[82:83], v[60:61]
	v_pk_fma_f32 v[54:55], v[54:55], v[84:85], v[64:65]
	v_cvt_pk_bf16_f32 v48, v48, v49
	v_cvt_pk_bf16_f32 v49, v52, v53
	v_cvt_pk_bf16_f32 v50, v50, v51
	v_cvt_pk_bf16_f32 v51, v54, v55
	global_store_dwordx4 v[86:87], v[48:51], off
	s_nop 1
	v_mov_b32_e32 v48, v142
	v_mov_b32_e32 v49, v143
	v_mov_b32_e32 v50, v144
	v_mov_b32_e32 v51, v145
	s_nop 0
	v_mov_b32_e32 v52, v138
	v_mov_b32_e32 v53, v139
	v_mov_b32_e32 v54, v140
	v_mov_b32_e32 v55, v141
	v_mov_b32_e32 v56, v154
	v_mov_b32_e32 v57, v155
	v_mov_b32_e32 v58, v156
	v_mov_b32_e32 v59, v157
	v_mov_b32_e32 v60, v158
	v_mov_b32_e32 v61, v159
	v_mov_b32_e32 v62, v160
	v_mov_b32_e32 v63, v161
	v_pk_mul_f32 v[64:65], v[92:93], v[70:71] op_sel_hi:[1,0]
	v_pk_mul_f32 v[78:79], v[96:97], v[70:71] op_sel_hi:[1,0]
	v_pk_mul_f32 v[80:81], v[94:95], v[70:71] op_sel_hi:[1,0]
	v_pk_mul_f32 v[82:83], v[98:99], v[70:71] op_sel_hi:[1,0]
	v_cndmask_b32_e32 v19, v66, v19, vcc
	v_rsq_f32_e32 v19, v19
	s_waitcnt vmcnt(1)
	v_pk_fma_f32 v[64:65], v[52:53], v[64:65], v[56:57]
	s_waitcnt vmcnt(1)
	v_pk_fma_f32 v[78:79], v[48:49], v[78:79], v[60:61]
	v_pk_fma_f32 v[80:81], v[54:55], v[80:81], v[58:59]
	v_pk_fma_f32 v[82:83], v[50:51], v[82:83], v[62:63]
	v_cvt_pk_bf16_f32 v48, v64, v65
	v_cvt_pk_bf16_f32 v49, v80, v81
	v_cvt_pk_bf16_f32 v50, v78, v79
	v_cvt_pk_bf16_f32 v51, v82, v83
	global_store_dwordx4 v[68:69], v[48:51], off offset:1024
	global_load_dwordx4 v[48:51], v[40:41], off
	s_nop 0
	global_load_dwordx4 v[52:55], v[40:41], off offset:16
	global_load_dwordx4 v[56:59], v[46:47], off
	global_load_dwordx4 v[60:63], v[46:47], off offset:16
	v_mul_f32_e32 v66, 0x45800000, v19
	v_cndmask_b32_e32 v66, v19, v66, vcc
	v_pk_mul_f32 v[10:11], v[10:11], v[66:67] op_sel_hi:[1,0]
	v_pk_mul_f32 v[16:17], v[16:17], v[66:67] op_sel_hi:[1,0]
	v_pk_mul_f32 v[12:13], v[12:13], v[66:67] op_sel_hi:[1,0]
	v_pk_mul_f32 v[14:15], v[14:15], v[66:67] op_sel_hi:[1,0]
	v_pk_mul_f32 v[4:5], v[4:5], v[66:67] op_sel_hi:[1,0]
	v_pk_mul_f32 v[6:7], v[6:7], v[66:67] op_sel_hi:[1,0]
	v_pk_mul_f32 v[2:3], v[2:3], v[66:67] op_sel_hi:[1,0]
	v_pk_mul_f32 v[8:9], v[8:9], v[66:67] op_sel_hi:[1,0]
	v_cmp_lt_i32_e32 vcc, s23, v18
	s_or_b64 s[4:5], vcc, s[4:5]
	s_waitcnt vmcnt(3)
	v_pk_add_f32 v[48:49], v[48:49], 1.0 op_sel_hi:[1,0]
	s_waitcnt vmcnt(2)
	v_pk_add_f32 v[52:53], v[52:53], 1.0 op_sel_hi:[1,0]
	v_pk_add_f32 v[50:51], v[50:51], 1.0 op_sel_hi:[1,0]
	v_pk_add_f32 v[54:55], v[54:55], 1.0 op_sel_hi:[1,0]
	s_waitcnt vmcnt(1)
	v_pk_fma_f32 v[48:49], v[48:49], v[64:65], v[56:57]
	s_waitcnt vmcnt(0)
	v_pk_fma_f32 v[52:53], v[52:53], v[78:79], v[60:61]
	v_pk_fma_f32 v[50:51], v[50:51], v[80:81], v[58:59]
	v_pk_fma_f32 v[54:55], v[54:55], v[82:83], v[62:63]
	v_cvt_pk_bf16_f32 v48, v48, v49
	v_cvt_pk_bf16_f32 v49, v50, v51
	v_cvt_pk_bf16_f32 v50, v52, v53
	v_cvt_pk_bf16_f32 v51, v54, v55
	global_store_dwordx4 v[86:87], v[48:51], off offset:1024
	s_nop 1
	v_mov_b32_e32 v48, v134
	v_mov_b32_e32 v49, v135
	v_mov_b32_e32 v50, v136
	v_mov_b32_e32 v51, v137
	s_nop 0
	v_mov_b32_e32 v52, v130
	v_mov_b32_e32 v53, v131
	v_mov_b32_e32 v54, v132
	v_mov_b32_e32 v55, v133
	v_mov_b32_e32 v56, v146
	v_mov_b32_e32 v57, v147
	v_mov_b32_e32 v58, v148
	v_mov_b32_e32 v59, v149
	v_mov_b32_e32 v60, v150
	v_mov_b32_e32 v61, v151
	v_mov_b32_e32 v62, v152
	v_mov_b32_e32 v63, v153
	v_lshl_add_u64 v[64:65], v[28:29], 0, v[38:39]
	v_lshl_add_u64 v[38:39], v[30:31], 0, v[38:39]
	s_waitcnt vmcnt(1)
	v_pk_fma_f32 v[56:57], v[52:53], v[10:11], v[56:57]
	s_waitcnt vmcnt(1)
	v_pk_fma_f32 v[60:61], v[48:49], v[16:17], v[60:61]
	v_pk_fma_f32 v[58:59], v[54:55], v[12:13], v[58:59]
	v_pk_fma_f32 v[62:63], v[50:51], v[14:15], v[62:63]
	v_cvt_pk_bf16_f32 v10, v56, v57
	v_cvt_pk_bf16_f32 v11, v58, v59
	v_cvt_pk_bf16_f32 v12, v60, v61
	v_cvt_pk_bf16_f32 v13, v62, v63
	global_store_dwordx4 v[64:65], v[10:13], off
	global_load_dwordx4 v[10:13], v[42:43], off
	s_nop 0
	global_load_dwordx4 v[14:17], v[42:43], off offset:16
	global_load_dwordx4 v[48:51], v[44:45], off
	global_load_dwordx4 v[52:55], v[44:45], off offset:16
	s_waitcnt vmcnt(3)
	v_pk_add_f32 v[10:11], v[10:11], 1.0 op_sel_hi:[1,0]
	s_waitcnt vmcnt(2)
	v_pk_add_f32 v[14:15], v[14:15], 1.0 op_sel_hi:[1,0]
	v_pk_add_f32 v[12:13], v[12:13], 1.0 op_sel_hi:[1,0]
	v_pk_add_f32 v[16:17], v[16:17], 1.0 op_sel_hi:[1,0]
	s_waitcnt vmcnt(1)
	v_pk_fma_f32 v[10:11], v[10:11], v[56:57], v[48:49]
	s_waitcnt vmcnt(0)
	v_pk_fma_f32 v[14:15], v[14:15], v[60:61], v[52:53]
	v_pk_fma_f32 v[12:13], v[12:13], v[58:59], v[50:51]
	v_pk_fma_f32 v[16:17], v[16:17], v[62:63], v[54:55]
	v_cvt_pk_bf16_f32 v10, v10, v11
	v_cvt_pk_bf16_f32 v11, v12, v13
	v_cvt_pk_bf16_f32 v12, v14, v15
	v_cvt_pk_bf16_f32 v13, v16, v17
	global_store_dwordx4 v[38:39], v[10:13], off
	s_nop 1
	v_mov_b32_e32 v10, v142
	v_mov_b32_e32 v11, v143
	v_mov_b32_e32 v12, v144
	v_mov_b32_e32 v13, v145
	s_nop 0
	v_mov_b32_e32 v14, v138
	v_mov_b32_e32 v15, v139
	v_mov_b32_e32 v16, v140
	v_mov_b32_e32 v17, v141
	v_mov_b32_e32 v42, v154
	v_mov_b32_e32 v43, v155
	v_mov_b32_e32 v44, v156
	v_mov_b32_e32 v45, v157
	v_mov_b32_e32 v48, v158
	v_mov_b32_e32 v49, v159
	v_mov_b32_e32 v50, v160
	v_mov_b32_e32 v51, v161
	s_waitcnt vmcnt(1)
	v_pk_fma_f32 v[42:43], v[14:15], v[4:5], v[42:43]
	s_waitcnt vmcnt(1)
	v_pk_fma_f32 v[48:49], v[10:11], v[6:7], v[48:49]
	v_pk_fma_f32 v[44:45], v[16:17], v[2:3], v[44:45]
	v_pk_fma_f32 v[50:51], v[12:13], v[8:9], v[50:51]
	v_cvt_pk_bf16_f32 v2, v42, v43
	v_cvt_pk_bf16_f32 v3, v44, v45
	v_cvt_pk_bf16_f32 v4, v48, v49
	v_cvt_pk_bf16_f32 v5, v50, v51
	global_store_dwordx4 v[64:65], v[2:5], off offset:1024
	global_load_dwordx4 v[2:5], v[40:41], off
	s_nop 0
	global_load_dwordx4 v[6:9], v[40:41], off offset:16
	global_load_dwordx4 v[10:13], v[46:47], off
	global_load_dwordx4 v[14:17], v[46:47], off offset:16
	s_waitcnt vmcnt(3)
	v_pk_add_f32 v[2:3], v[2:3], 1.0 op_sel_hi:[1,0]
	s_waitcnt vmcnt(2)
	v_pk_add_f32 v[6:7], v[6:7], 1.0 op_sel_hi:[1,0]
	v_pk_add_f32 v[4:5], v[4:5], 1.0 op_sel_hi:[1,0]
	v_pk_add_f32 v[8:9], v[8:9], 1.0 op_sel_hi:[1,0]
	s_waitcnt vmcnt(1)
	v_pk_fma_f32 v[2:3], v[2:3], v[42:43], v[10:11]
	s_waitcnt vmcnt(0)
	v_pk_fma_f32 v[6:7], v[6:7], v[48:49], v[14:15]
	v_pk_fma_f32 v[4:5], v[4:5], v[44:45], v[12:13]
	v_pk_fma_f32 v[8:9], v[8:9], v[50:51], v[16:17]
	v_cvt_pk_bf16_f32 v2, v2, v3
	v_cvt_pk_bf16_f32 v3, v4, v5
	v_cvt_pk_bf16_f32 v4, v6, v7
	v_cvt_pk_bf16_f32 v5, v8, v9
	global_store_dwordx4 v[38:39], v[2:5], off offset:1024
	s_andn2_b64 exec, exec, s[4:5]
	s_cbranch_execnz .LBB0_1364
